# grid barrier: the L1 invalidate (buffer_inv sc1) is issued right behind the arrival atomic and overlaps the wait; no cached load happens on the CU between it and the barrier exit
# speedup vs baseline: 1.0535x; 1.0021x over previous
; __device__ __forceinline__ unsigned xb_ld(unsigned* p)              { return __hip_atomic_load(p, __ATOMIC_RELAXED, __HIP_MEMORY_SCOPE_AGENT); }
; __device__ __forceinline__ unsigned xb_add(unsigned* p, unsigned v) { return __hip_atomic_fetch_add(p, v, __ATOMIC_RELAXED, __HIP_MEMORY_SCOPE_AGENT); }
; #define XB_SPIN(cond, bar) do { unsigned _sp = 0; while (cond) { __builtin_amdgcn_s_sleep(1); \
;     if ((++_sp & 255u) == 0u) { if (xb_ld(&(bar)[XB_TMO])) break; if (_sp > XB_SPIN_CAP) { atomicAdd(&(bar)[XB_TMO], 1u); break; } } } } while (0)
; __device__ __forceinline__ void xcd_barrier(const XcdBarrier& b) {
;     ...
;         const unsigned old = xb_add(&bar[XB_XSUB(b.x)], 1u);
;         const unsigned gen = old / nloc;
;         if (old + 1u == (gen + 1u) * nloc) {
;             __builtin_amdgcn_fence(__ATOMIC_RELEASE, "agent");
;             asm volatile("s_waitcnt vmcnt(0)" ::: "memory");
;             const unsigned og = xb_add(&bar[XB_TOP], 1u);
;             const unsigned tg = og / nx;
;             if (og + 1u == (tg + 1u) * nx) xb_add(&bar[XB_TOPGEN], 1u);
;             else XB_SPIN(xb_ld(&bar[XB_TOPGEN]) == tg, bar);
;             __builtin_amdgcn_fence(__ATOMIC_ACQUIRE, "agent");
;             xb_add(&bar[XB_XGEN(b.x)], 1u);
;             asm volatile("s_waitcnt vmcnt(0)" ::: "memory");
;         } else {
;             XB_SPIN(xb_ld(&bar[XB_XGEN(b.x)]) == gen, bar);
.LBB0_54:
	s_or_b64 exec, exec, s[8:9]
	buffer_inv sc1
	v_cvt_f32_u32_e32 v4, v2
	s_waitcnt vmcnt(0)
	v_readfirstlane_b32 s0, v3
	v_sub_u32_e32 v3, 0, v2
	v_rcp_iflag_f32_e32 v4, v4
	v_add_u32_e32 v5, s0, v1
	v_mul_f32_e32 v4, 0x4f7ffffe, v4
	v_cvt_u32_f32_e32 v4, v4
	v_mul_lo_u32 v1, v3, v4
	v_mul_hi_u32 v1, v4, v1
	v_add_u32_e32 v1, v4, v1
	v_mul_hi_u32 v1, v5, v1
	v_mul_lo_u32 v3, v1, v2
	v_sub_u32_e32 v3, v5, v3
	v_add_u32_e32 v4, 1, v1
	v_cmp_ge_u32_e32 vcc, v3, v2
	s_nop 1
	v_cndmask_b32_e32 v1, v1, v4, vcc
	v_sub_u32_e32 v4, v3, v2
	v_cndmask_b32_e32 v3, v3, v4, vcc
	v_add_u32_e32 v4, 1, v1
	v_cmp_ge_u32_e32 vcc, v3, v2
	v_add_u32_e32 v3, 1, v5
	s_nop 0
	v_cndmask_b32_e32 v1, v1, v4, vcc
	v_mul_lo_u32 v4, v2, v1
	v_add_u32_e32 v2, v4, v2
	v_cmp_ne_u32_e32 vcc, v3, v2
	s_and_saveexec_b64 s[0:1], vcc
	s_xor_b64 s[0:1], exec, s[0:1]
	s_cbranch_execz .LBB0_68
	s_waitcnt lgkmcnt(0)
	v_mov_b32_e32 v0, 0x2000
	global_load_dword v0, v0, s[6:7] offset:1024 sc1
	s_add_u32 s12, s6, 0x2400
	s_addc_u32 s13, s7, 0
	s_waitcnt vmcnt(0)
	v_cmp_eq_u32_e32 vcc, v0, v1
	s_and_saveexec_b64 s[8:9], vcc
	s_cbranch_execz .LBB0_67
	s_add_u32 s10, s84, 0xc10200
	s_addc_u32 s11, s85, 0
	s_mov_b32 s3, 1
	s_mov_b64 s[14:15], 0
	v_mov_b32_e32 v0, 0
	s_branch .LBB0_58

; __device__ __forceinline__ void xcd_barrier(const XcdBarrier& b) {
;     ...
;             __builtin_amdgcn_fence(__ATOMIC_ACQUIRE, "agent");
;             asm volatile("s_waitcnt vmcnt(0)" ::: "memory");
.LBB0_67:
	s_or_b64 exec, exec, s[8:9]
	s_waitcnt vmcnt(0)
	s_nop 0
	s_waitcnt vmcnt(0)

; __device__ __forceinline__ unsigned xb_ld(unsigned* p)              { return __hip_atomic_load(p, __ATOMIC_RELAXED, __HIP_MEMORY_SCOPE_AGENT); }
; __device__ __forceinline__ unsigned xb_add(unsigned* p, unsigned v) { return __hip_atomic_fetch_add(p, v, __ATOMIC_RELAXED, __HIP_MEMORY_SCOPE_AGENT); }
; #define XB_SPIN(cond, bar) do { unsigned _sp = 0; while (cond) { __builtin_amdgcn_s_sleep(1); \
;     if ((++_sp & 255u) == 0u) { if (xb_ld(&(bar)[XB_TMO])) break; if (_sp > XB_SPIN_CAP) { atomicAdd(&(bar)[XB_TMO], 1u); break; } } } } while (0)
; __device__ __forceinline__ void xcd_barrier(const XcdBarrier& b) {
;     ...
;             if (og + 1u == (tg + 1u) * nx) xb_add(&bar[XB_TOPGEN], 1u);
;             else XB_SPIN(xb_ld(&bar[XB_TOPGEN]) == tg, bar);
;             __builtin_amdgcn_fence(__ATOMIC_ACQUIRE, "agent");
;             xb_add(&bar[XB_XGEN(b.x)], 1u);
;             asm volatile("s_waitcnt vmcnt(0)" ::: "memory");
.LBB0_85:
	s_or_b64 exec, exec, s[0:1]
	s_mov_b64 s[0:1], exec
	v_mbcnt_lo_u32_b32 v0, s0, 0
	v_mbcnt_hi_u32_b32 v0, s1, v0
	v_cmp_eq_u32_e32 vcc, 0, v0
	s_waitcnt vmcnt(0)
	s_nop 0
	s_and_saveexec_b64 s[8:9], vcc
	s_cbranch_execz .LBB0_87
	s_bcnt1_i32_b64 s0, s[0:1]
	v_mov_b32_e32 v0, 0x2000
	v_mov_b32_e32 v1, s0
	s_nop 0

; __device__ __forceinline__ unsigned xb_ld(unsigned* p)              { return __hip_atomic_load(p, __ATOMIC_RELAXED, __HIP_MEMORY_SCOPE_AGENT); }
; __device__ __forceinline__ unsigned xb_add(unsigned* p, unsigned v) { return __hip_atomic_fetch_add(p, v, __ATOMIC_RELAXED, __HIP_MEMORY_SCOPE_AGENT); }
; #define XB_SPIN(cond, bar) do { unsigned _sp = 0; while (cond) { __builtin_amdgcn_s_sleep(1); \
;     if ((++_sp & 255u) == 0u) { if (xb_ld(&(bar)[XB_TMO])) break; if (_sp > XB_SPIN_CAP) { atomicAdd(&(bar)[XB_TMO], 1u); break; } } } } while (0)
; __device__ __forceinline__ void xcd_barrier(const XcdBarrier& b) {
;     ...
;         const unsigned old = xb_add(&bar[XB_XSUB(b.x)], 1u);
;         const unsigned gen = old / nloc;
;         if (old + 1u == (gen + 1u) * nloc) {
;             __builtin_amdgcn_fence(__ATOMIC_RELEASE, "agent");
;             asm volatile("s_waitcnt vmcnt(0)" ::: "memory");
;             const unsigned og = xb_add(&bar[XB_TOP], 1u);
;             const unsigned tg = og / nx;
;             if (og + 1u == (tg + 1u) * nx) xb_add(&bar[XB_TOPGEN], 1u);
;             else XB_SPIN(xb_ld(&bar[XB_TOPGEN]) == tg, bar);
;             __builtin_amdgcn_fence(__ATOMIC_ACQUIRE, "agent");
;             xb_add(&bar[XB_XGEN(b.x)], 1u);
;             asm volatile("s_waitcnt vmcnt(0)" ::: "memory");
;         } else {
;             XB_SPIN(xb_ld(&bar[XB_XGEN(b.x)]) == gen, bar);
.LBB0_494:
	s_or_b64 exec, exec, s[12:13]
	buffer_inv sc1
	v_cvt_f32_u32_e32 v4, v2
	s_waitcnt vmcnt(0)
	v_readfirstlane_b32 s0, v3
	v_sub_u32_e32 v3, 0, v2
	v_rcp_iflag_f32_e32 v4, v4
	v_add_u32_e32 v5, s0, v1
	v_mul_f32_e32 v4, 0x4f7ffffe, v4
	v_cvt_u32_f32_e32 v4, v4
	v_mul_lo_u32 v1, v3, v4
	v_mul_hi_u32 v1, v4, v1
	v_add_u32_e32 v1, v4, v1
	v_mul_hi_u32 v1, v5, v1
	v_mul_lo_u32 v3, v1, v2
	v_sub_u32_e32 v3, v5, v3
	v_add_u32_e32 v4, 1, v1
	v_cmp_ge_u32_e32 vcc, v3, v2
	s_nop 1
	v_cndmask_b32_e32 v1, v1, v4, vcc
	v_sub_u32_e32 v4, v3, v2
	v_cndmask_b32_e32 v3, v3, v4, vcc
	v_add_u32_e32 v4, 1, v1
	v_cmp_ge_u32_e32 vcc, v3, v2
	v_add_u32_e32 v3, 1, v5
	s_nop 0
	v_cndmask_b32_e32 v1, v1, v4, vcc
	v_mul_lo_u32 v4, v2, v1
	v_add_u32_e32 v2, v4, v2
	v_cmp_ne_u32_e32 vcc, v3, v2
	s_and_saveexec_b64 s[0:1], vcc
	s_xor_b64 s[0:1], exec, s[0:1]
	s_cbranch_execz .LBB0_508
	s_waitcnt lgkmcnt(0)
	v_mov_b32_e32 v0, 0x2000
	global_load_dword v0, v0, s[10:11] offset:1024 sc1
	s_add_u32 s18, s10, 0x2400
	s_addc_u32 s19, s11, 0
	s_waitcnt vmcnt(0)
	v_cmp_eq_u32_e32 vcc, v0, v1
	s_and_saveexec_b64 s[12:13], vcc
	s_cbranch_execz .LBB0_507
	s_add_u32 s14, s84, 0xc10200
	s_addc_u32 s15, s85, 0
	s_mov_b32 s4, 1
	s_mov_b64 s[44:45], 0
	v_mov_b32_e32 v0, 0
	s_branch .LBB0_498

; __device__ __forceinline__ void xcd_barrier(const XcdBarrier& b) {
;     ...
;             __builtin_amdgcn_fence(__ATOMIC_ACQUIRE, "agent");
;             asm volatile("s_waitcnt vmcnt(0)" ::: "memory");
.LBB0_507:
	s_or_b64 exec, exec, s[12:13]
	s_waitcnt vmcnt(0)
	s_nop 0
	s_waitcnt vmcnt(0)

; __device__ __forceinline__ unsigned xb_ld(unsigned* p)              { return __hip_atomic_load(p, __ATOMIC_RELAXED, __HIP_MEMORY_SCOPE_AGENT); }
; __device__ __forceinline__ unsigned xb_add(unsigned* p, unsigned v) { return __hip_atomic_fetch_add(p, v, __ATOMIC_RELAXED, __HIP_MEMORY_SCOPE_AGENT); }
; #define XB_SPIN(cond, bar) do { unsigned _sp = 0; while (cond) { __builtin_amdgcn_s_sleep(1); \
;     if ((++_sp & 255u) == 0u) { if (xb_ld(&(bar)[XB_TMO])) break; if (_sp > XB_SPIN_CAP) { atomicAdd(&(bar)[XB_TMO], 1u); break; } } } } while (0)
; __device__ __forceinline__ void xcd_barrier(const XcdBarrier& b) {
;     ...
;             if (og + 1u == (tg + 1u) * nx) xb_add(&bar[XB_TOPGEN], 1u);
;             else XB_SPIN(xb_ld(&bar[XB_TOPGEN]) == tg, bar);
;             __builtin_amdgcn_fence(__ATOMIC_ACQUIRE, "agent");
;             xb_add(&bar[XB_XGEN(b.x)], 1u);
;             asm volatile("s_waitcnt vmcnt(0)" ::: "memory");
.LBB0_525:
	s_or_b64 exec, exec, s[0:1]
	s_mov_b64 s[0:1], exec
	v_mbcnt_lo_u32_b32 v0, s0, 0
	v_mbcnt_hi_u32_b32 v0, s1, v0
	v_cmp_eq_u32_e32 vcc, 0, v0
	s_waitcnt vmcnt(0)
	s_nop 0
	s_and_saveexec_b64 s[12:13], vcc
	s_cbranch_execz .LBB0_527
	s_bcnt1_i32_b64 s0, s[0:1]
	v_mov_b32_e32 v0, 0x2000
	v_mov_b32_e32 v1, s0
	s_nop 0

; __device__ __forceinline__ unsigned xb_ld(unsigned* p)              { return __hip_atomic_load(p, __ATOMIC_RELAXED, __HIP_MEMORY_SCOPE_AGENT); }
; __device__ __forceinline__ unsigned xb_add(unsigned* p, unsigned v) { return __hip_atomic_fetch_add(p, v, __ATOMIC_RELAXED, __HIP_MEMORY_SCOPE_AGENT); }
; #define XB_SPIN(cond, bar) do { unsigned _sp = 0; while (cond) { __builtin_amdgcn_s_sleep(1); \
;     if ((++_sp & 255u) == 0u) { if (xb_ld(&(bar)[XB_TMO])) break; if (_sp > XB_SPIN_CAP) { atomicAdd(&(bar)[XB_TMO], 1u); break; } } } } while (0)
; __device__ __forceinline__ void xcd_barrier(const XcdBarrier& b) {
;     ...
;         const unsigned old = xb_add(&bar[XB_XSUB(b.x)], 1u);
;         const unsigned gen = old / nloc;
;         if (old + 1u == (gen + 1u) * nloc) {
;             __builtin_amdgcn_fence(__ATOMIC_RELEASE, "agent");
;             asm volatile("s_waitcnt vmcnt(0)" ::: "memory");
;             const unsigned og = xb_add(&bar[XB_TOP], 1u);
;             const unsigned tg = og / nx;
;             if (og + 1u == (tg + 1u) * nx) xb_add(&bar[XB_TOPGEN], 1u);
;             else XB_SPIN(xb_ld(&bar[XB_TOPGEN]) == tg, bar);
;             __builtin_amdgcn_fence(__ATOMIC_ACQUIRE, "agent");
;             xb_add(&bar[XB_XGEN(b.x)], 1u);
;             asm volatile("s_waitcnt vmcnt(0)" ::: "memory");
;         } else {
;             XB_SPIN(xb_ld(&bar[XB_XGEN(b.x)]) == gen, bar);
.LBB0_824:
	s_or_b64 exec, exec, s[10:11]
	buffer_inv sc1
	v_cvt_f32_u32_e32 v4, v2
	s_waitcnt vmcnt(0)
	v_readfirstlane_b32 s0, v3
	v_sub_u32_e32 v3, 0, v2
	v_rcp_iflag_f32_e32 v4, v4
	v_add_u32_e32 v5, s0, v1
	v_mul_f32_e32 v4, 0x4f7ffffe, v4
	v_cvt_u32_f32_e32 v4, v4
	v_mul_lo_u32 v1, v3, v4
	v_mul_hi_u32 v1, v4, v1
	v_add_u32_e32 v1, v4, v1
	v_mul_hi_u32 v1, v5, v1
	v_mul_lo_u32 v3, v1, v2
	v_sub_u32_e32 v3, v5, v3
	v_add_u32_e32 v4, 1, v1
	v_cmp_ge_u32_e32 vcc, v3, v2
	s_nop 1
	v_cndmask_b32_e32 v1, v1, v4, vcc
	v_sub_u32_e32 v4, v3, v2
	v_cndmask_b32_e32 v3, v3, v4, vcc
	v_add_u32_e32 v4, 1, v1
	v_cmp_ge_u32_e32 vcc, v3, v2
	v_add_u32_e32 v3, 1, v5
	s_nop 0
	v_cndmask_b32_e32 v1, v1, v4, vcc
	v_mul_lo_u32 v4, v2, v1
	v_add_u32_e32 v2, v4, v2
	v_cmp_ne_u32_e32 vcc, v3, v2
	s_and_saveexec_b64 s[0:1], vcc
	s_xor_b64 s[0:1], exec, s[0:1]
	s_cbranch_execz .LBB0_838
	s_waitcnt lgkmcnt(0)
	v_mov_b32_e32 v0, 0x2000
	global_load_dword v0, v0, s[8:9] offset:1024 sc1
	s_add_u32 s14, s8, 0x2400
	s_addc_u32 s15, s9, 0
	s_waitcnt vmcnt(0)
	v_cmp_eq_u32_e32 vcc, v0, v1
	s_and_saveexec_b64 s[10:11], vcc
	s_cbranch_execz .LBB0_837
	s_add_u32 s12, s84, 0xc10200
	s_addc_u32 s13, s85, 0
	s_mov_b32 s4, 1
	s_mov_b64 s[18:19], 0
	v_mov_b32_e32 v0, 0
	s_branch .LBB0_828

; __device__ __forceinline__ void xcd_barrier(const XcdBarrier& b) {
;     ...
;             __builtin_amdgcn_fence(__ATOMIC_ACQUIRE, "agent");
;             asm volatile("s_waitcnt vmcnt(0)" ::: "memory");
.LBB0_837:
	s_or_b64 exec, exec, s[10:11]
	s_waitcnt vmcnt(0)
	s_nop 0
	s_waitcnt vmcnt(0)

; __device__ __forceinline__ unsigned xb_ld(unsigned* p)              { return __hip_atomic_load(p, __ATOMIC_RELAXED, __HIP_MEMORY_SCOPE_AGENT); }
; __device__ __forceinline__ unsigned xb_add(unsigned* p, unsigned v) { return __hip_atomic_fetch_add(p, v, __ATOMIC_RELAXED, __HIP_MEMORY_SCOPE_AGENT); }
; #define XB_SPIN(cond, bar) do { unsigned _sp = 0; while (cond) { __builtin_amdgcn_s_sleep(1); \
;     if ((++_sp & 255u) == 0u) { if (xb_ld(&(bar)[XB_TMO])) break; if (_sp > XB_SPIN_CAP) { atomicAdd(&(bar)[XB_TMO], 1u); break; } } } } while (0)
; __device__ __forceinline__ void xcd_barrier(const XcdBarrier& b) {
;     ...
;             if (og + 1u == (tg + 1u) * nx) xb_add(&bar[XB_TOPGEN], 1u);
;             else XB_SPIN(xb_ld(&bar[XB_TOPGEN]) == tg, bar);
;             __builtin_amdgcn_fence(__ATOMIC_ACQUIRE, "agent");
;             xb_add(&bar[XB_XGEN(b.x)], 1u);
;             asm volatile("s_waitcnt vmcnt(0)" ::: "memory");
.LBB0_855:
	s_or_b64 exec, exec, s[0:1]
	s_mov_b64 s[0:1], exec
	v_mbcnt_lo_u32_b32 v0, s0, 0
	v_mbcnt_hi_u32_b32 v0, s1, v0
	v_cmp_eq_u32_e32 vcc, 0, v0
	s_waitcnt vmcnt(0)
	s_nop 0
	s_and_saveexec_b64 s[10:11], vcc
	s_cbranch_execz .LBB0_857
	s_bcnt1_i32_b64 s0, s[0:1]
	v_mov_b32_e32 v0, 0x2000
	v_mov_b32_e32 v1, s0
	s_nop 0

; __device__ __forceinline__ unsigned xb_ld(unsigned* p)              { return __hip_atomic_load(p, __ATOMIC_RELAXED, __HIP_MEMORY_SCOPE_AGENT); }
; __device__ __forceinline__ unsigned xb_add(unsigned* p, unsigned v) { return __hip_atomic_fetch_add(p, v, __ATOMIC_RELAXED, __HIP_MEMORY_SCOPE_AGENT); }
; #define XB_SPIN(cond, bar) do { unsigned _sp = 0; while (cond) { __builtin_amdgcn_s_sleep(1); \
;     if ((++_sp & 255u) == 0u) { if (xb_ld(&(bar)[XB_TMO])) break; if (_sp > XB_SPIN_CAP) { atomicAdd(&(bar)[XB_TMO], 1u); break; } } } } while (0)
; __device__ __forceinline__ void xcd_barrier(const XcdBarrier& b) {
;     ...
;         const unsigned old = xb_add(&bar[XB_XSUB(b.x)], 1u);
;         const unsigned gen = old / nloc;
;         if (old + 1u == (gen + 1u) * nloc) {
;             __builtin_amdgcn_fence(__ATOMIC_RELEASE, "agent");
;             asm volatile("s_waitcnt vmcnt(0)" ::: "memory");
;             const unsigned og = xb_add(&bar[XB_TOP], 1u);
;             const unsigned tg = og / nx;
;             if (og + 1u == (tg + 1u) * nx) xb_add(&bar[XB_TOPGEN], 1u);
;             else XB_SPIN(xb_ld(&bar[XB_TOPGEN]) == tg, bar);
;             __builtin_amdgcn_fence(__ATOMIC_ACQUIRE, "agent");
;             xb_add(&bar[XB_XGEN(b.x)], 1u);
;             asm volatile("s_waitcnt vmcnt(0)" ::: "memory");
;         } else {
;             XB_SPIN(xb_ld(&bar[XB_XGEN(b.x)]) == gen, bar);
.LBB0_898:
	s_or_b64 exec, exec, s[8:9]
	buffer_inv sc1
	v_cvt_f32_u32_e32 v4, v2
	s_waitcnt vmcnt(0)
	v_readfirstlane_b32 s0, v3
	v_sub_u32_e32 v3, 0, v2
	v_rcp_iflag_f32_e32 v4, v4
	v_add_u32_e32 v5, s0, v1
	v_mul_f32_e32 v4, 0x4f7ffffe, v4
	v_cvt_u32_f32_e32 v4, v4
	v_mul_lo_u32 v1, v3, v4
	v_mul_hi_u32 v1, v4, v1
	v_add_u32_e32 v1, v4, v1
	v_mul_hi_u32 v1, v5, v1
	v_mul_lo_u32 v3, v1, v2
	v_sub_u32_e32 v3, v5, v3
	v_add_u32_e32 v4, 1, v1
	v_cmp_ge_u32_e32 vcc, v3, v2
	s_nop 1
	v_cndmask_b32_e32 v1, v1, v4, vcc
	v_sub_u32_e32 v4, v3, v2
	v_cndmask_b32_e32 v3, v3, v4, vcc
	v_add_u32_e32 v4, 1, v1
	v_cmp_ge_u32_e32 vcc, v3, v2
	v_add_u32_e32 v3, 1, v5
	s_nop 0
	v_cndmask_b32_e32 v1, v1, v4, vcc
	v_mul_lo_u32 v4, v2, v1
	v_add_u32_e32 v2, v4, v2
	v_cmp_ne_u32_e32 vcc, v3, v2
	s_and_saveexec_b64 s[0:1], vcc
	s_xor_b64 s[0:1], exec, s[0:1]
	s_cbranch_execz .LBB0_912
	s_waitcnt lgkmcnt(0)
	v_mov_b32_e32 v0, 0x2000
	global_load_dword v0, v0, s[6:7] offset:1024 sc1
	s_add_u32 s12, s6, 0x2400
	s_addc_u32 s13, s7, 0
	s_waitcnt vmcnt(0)
	v_cmp_eq_u32_e32 vcc, v0, v1
	s_and_saveexec_b64 s[8:9], vcc
	s_cbranch_execz .LBB0_911
	s_add_u32 s10, s84, 0xc10200
	s_addc_u32 s11, s85, 0
	s_mov_b32 s16, 1
	s_mov_b64 s[14:15], 0
	v_mov_b32_e32 v0, 0
	s_branch .LBB0_902

; __device__ __forceinline__ unsigned xb_ld(unsigned* p)              { return __hip_atomic_load(p, __ATOMIC_RELAXED, __HIP_MEMORY_SCOPE_AGENT); }
; __device__ __forceinline__ unsigned xb_add(unsigned* p, unsigned v) { return __hip_atomic_fetch_add(p, v, __ATOMIC_RELAXED, __HIP_MEMORY_SCOPE_AGENT); }
; #define XB_SPIN(cond, bar) do { unsigned _sp = 0; while (cond) { __builtin_amdgcn_s_sleep(1); \
;     if ((++_sp & 255u) == 0u) { if (xb_ld(&(bar)[XB_TMO])) break; if (_sp > XB_SPIN_CAP) { atomicAdd(&(bar)[XB_TMO], 1u); break; } } } } while (0)
; __device__ __forceinline__ void xcd_barrier(const XcdBarrier& b) {
;     ...
;         const unsigned old = xb_add(&bar[XB_XSUB(b.x)], 1u);
;         const unsigned gen = old / nloc;
;         if (old + 1u == (gen + 1u) * nloc) {
;             __builtin_amdgcn_fence(__ATOMIC_RELEASE, "agent");
;             asm volatile("s_waitcnt vmcnt(0)" ::: "memory");
;             const unsigned og = xb_add(&bar[XB_TOP], 1u);
;             const unsigned tg = og / nx;
;             if (og + 1u == (tg + 1u) * nx) xb_add(&bar[XB_TOPGEN], 1u);
;             else XB_SPIN(xb_ld(&bar[XB_TOPGEN]) == tg, bar);
;             __builtin_amdgcn_fence(__ATOMIC_ACQUIRE, "agent");
;             xb_add(&bar[XB_XGEN(b.x)], 1u);
;             asm volatile("s_waitcnt vmcnt(0)" ::: "memory");
;         } else {
;             XB_SPIN(xb_ld(&bar[XB_XGEN(b.x)]) == gen, bar);
.LBB0_1004:
	s_or_b64 exec, exec, s[12:13]
	buffer_inv sc1
	v_cvt_f32_u32_e32 v4, v2
	s_waitcnt vmcnt(0)
	v_readfirstlane_b32 s0, v3
	v_sub_u32_e32 v3, 0, v2
	v_rcp_iflag_f32_e32 v4, v4
	v_add_u32_e32 v5, s0, v1
	v_mul_f32_e32 v4, 0x4f7ffffe, v4
	v_cvt_u32_f32_e32 v4, v4
	v_mul_lo_u32 v1, v3, v4
	v_mul_hi_u32 v1, v4, v1
	v_add_u32_e32 v1, v4, v1
	v_mul_hi_u32 v1, v5, v1
	v_mul_lo_u32 v3, v1, v2
	v_sub_u32_e32 v3, v5, v3
	v_add_u32_e32 v4, 1, v1
	v_cmp_ge_u32_e32 vcc, v3, v2
	s_nop 1
	v_cndmask_b32_e32 v1, v1, v4, vcc
	v_sub_u32_e32 v4, v3, v2
	v_cndmask_b32_e32 v3, v3, v4, vcc
	v_add_u32_e32 v4, 1, v1
	v_cmp_ge_u32_e32 vcc, v3, v2
	v_add_u32_e32 v3, 1, v5
	s_nop 0
	v_cndmask_b32_e32 v1, v1, v4, vcc
	v_mul_lo_u32 v4, v2, v1
	v_add_u32_e32 v2, v4, v2
	v_cmp_ne_u32_e32 vcc, v3, v2
	s_and_saveexec_b64 s[0:1], vcc
	s_xor_b64 s[0:1], exec, s[0:1]
	s_cbranch_execz .LBB0_1018
	s_waitcnt lgkmcnt(0)
	v_mov_b32_e32 v0, 0x2000
	global_load_dword v0, v0, s[10:11] offset:1024 sc1
	s_add_u32 s18, s10, 0x2400
	s_addc_u32 s19, s11, 0
	s_waitcnt vmcnt(0)
	v_cmp_eq_u32_e32 vcc, v0, v1
	s_and_saveexec_b64 s[12:13], vcc
	s_cbranch_execz .LBB0_1017
	s_add_u32 s14, s84, 0xc10200
	s_addc_u32 s15, s85, 0
	s_mov_b32 s4, 1
	s_mov_b64 s[46:47], 0
	v_mov_b32_e32 v0, 0
	s_branch .LBB0_1008

; __device__ __forceinline__ unsigned xb_ld(unsigned* p)              { return __hip_atomic_load(p, __ATOMIC_RELAXED, __HIP_MEMORY_SCOPE_AGENT); }
; __device__ __forceinline__ unsigned xb_add(unsigned* p, unsigned v) { return __hip_atomic_fetch_add(p, v, __ATOMIC_RELAXED, __HIP_MEMORY_SCOPE_AGENT); }
; #define XB_SPIN(cond, bar) do { unsigned _sp = 0; while (cond) { __builtin_amdgcn_s_sleep(1); \
;     if ((++_sp & 255u) == 0u) { if (xb_ld(&(bar)[XB_TMO])) break; if (_sp > XB_SPIN_CAP) { atomicAdd(&(bar)[XB_TMO], 1u); break; } } } } while (0)
; __device__ __forceinline__ void xcd_barrier(const XcdBarrier& b) {
;     ...
;         const unsigned old = xb_add(&bar[XB_XSUB(b.x)], 1u);
;         const unsigned gen = old / nloc;
;         if (old + 1u == (gen + 1u) * nloc) {
;             __builtin_amdgcn_fence(__ATOMIC_RELEASE, "agent");
;             asm volatile("s_waitcnt vmcnt(0)" ::: "memory");
;             const unsigned og = xb_add(&bar[XB_TOP], 1u);
;             const unsigned tg = og / nx;
;             if (og + 1u == (tg + 1u) * nx) xb_add(&bar[XB_TOPGEN], 1u);
;             else XB_SPIN(xb_ld(&bar[XB_TOPGEN]) == tg, bar);
;             __builtin_amdgcn_fence(__ATOMIC_ACQUIRE, "agent");
;             xb_add(&bar[XB_XGEN(b.x)], 1u);
;             asm volatile("s_waitcnt vmcnt(0)" ::: "memory");
;         } else {
;             XB_SPIN(xb_ld(&bar[XB_XGEN(b.x)]) == gen, bar);
.LBB0_1076:
	s_or_b64 exec, exec, s[14:15]
	buffer_inv sc1
	v_cvt_f32_u32_e32 v4, v2
	s_waitcnt vmcnt(0)
	v_readfirstlane_b32 s0, v3
	v_sub_u32_e32 v3, 0, v2
	v_rcp_iflag_f32_e32 v4, v4
	v_add_u32_e32 v5, s0, v1
	v_mul_f32_e32 v4, 0x4f7ffffe, v4
	v_cvt_u32_f32_e32 v4, v4
	v_mul_lo_u32 v1, v3, v4
	v_mul_hi_u32 v1, v4, v1
	v_add_u32_e32 v1, v4, v1
	v_mul_hi_u32 v1, v5, v1
	v_mul_lo_u32 v3, v1, v2
	v_sub_u32_e32 v3, v5, v3
	v_add_u32_e32 v4, 1, v1
	v_cmp_ge_u32_e32 vcc, v3, v2
	s_nop 1
	v_cndmask_b32_e32 v1, v1, v4, vcc
	v_sub_u32_e32 v4, v3, v2
	v_cndmask_b32_e32 v3, v3, v4, vcc
	v_add_u32_e32 v4, 1, v1
	v_cmp_ge_u32_e32 vcc, v3, v2
	v_add_u32_e32 v3, 1, v5
	s_nop 0
	v_cndmask_b32_e32 v1, v1, v4, vcc
	v_mul_lo_u32 v4, v2, v1
	v_add_u32_e32 v2, v4, v2
	v_cmp_ne_u32_e32 vcc, v3, v2
	s_and_saveexec_b64 s[0:1], vcc
	s_xor_b64 s[0:1], exec, s[0:1]
	s_cbranch_execz .LBB0_1090
	s_waitcnt lgkmcnt(0)
	v_mov_b32_e32 v0, 0x2000
	global_load_dword v0, v0, s[12:13] offset:1024 sc1
	s_add_u32 s46, s12, 0x2400
	s_addc_u32 s47, s13, 0
	s_waitcnt vmcnt(0)
	v_cmp_eq_u32_e32 vcc, v0, v1
	s_and_saveexec_b64 s[14:15], vcc
	s_cbranch_execz .LBB0_1089
	s_add_u32 s18, s84, 0xc10200
	s_addc_u32 s19, s85, 0
	s_mov_b32 s4, 1
	s_mov_b64 s[48:49], 0
	v_mov_b32_e32 v0, 0
	s_branch .LBB0_1080

; __device__ __forceinline__ void xcd_barrier(const XcdBarrier& b) {
;     ...
;             __builtin_amdgcn_fence(__ATOMIC_ACQUIRE, "agent");
;             asm volatile("s_waitcnt vmcnt(0)" ::: "memory");
.LBB0_1089:
	s_or_b64 exec, exec, s[14:15]
	s_waitcnt vmcnt(0)
	s_nop 0
	s_waitcnt vmcnt(0)

; __device__ __forceinline__ unsigned xb_ld(unsigned* p)              { return __hip_atomic_load(p, __ATOMIC_RELAXED, __HIP_MEMORY_SCOPE_AGENT); }
; __device__ __forceinline__ unsigned xb_add(unsigned* p, unsigned v) { return __hip_atomic_fetch_add(p, v, __ATOMIC_RELAXED, __HIP_MEMORY_SCOPE_AGENT); }
; #define XB_SPIN(cond, bar) do { unsigned _sp = 0; while (cond) { __builtin_amdgcn_s_sleep(1); \
;     if ((++_sp & 255u) == 0u) { if (xb_ld(&(bar)[XB_TMO])) break; if (_sp > XB_SPIN_CAP) { atomicAdd(&(bar)[XB_TMO], 1u); break; } } } } while (0)
; __device__ __forceinline__ void xcd_barrier(const XcdBarrier& b) {
;     ...
;             if (og + 1u == (tg + 1u) * nx) xb_add(&bar[XB_TOPGEN], 1u);
;             else XB_SPIN(xb_ld(&bar[XB_TOPGEN]) == tg, bar);
;             __builtin_amdgcn_fence(__ATOMIC_ACQUIRE, "agent");
;             xb_add(&bar[XB_XGEN(b.x)], 1u);
;             asm volatile("s_waitcnt vmcnt(0)" ::: "memory");
.LBB0_1107:
	s_or_b64 exec, exec, s[0:1]
	s_mov_b64 s[0:1], exec
	v_mbcnt_lo_u32_b32 v0, s0, 0
	v_mbcnt_hi_u32_b32 v0, s1, v0
	v_cmp_eq_u32_e32 vcc, 0, v0
	s_waitcnt vmcnt(0)
	s_nop 0
	s_and_saveexec_b64 s[14:15], vcc
	s_cbranch_execz .LBB0_1109
	s_bcnt1_i32_b64 s0, s[0:1]
	v_mov_b32_e32 v0, 0x2000
	v_mov_b32_e32 v1, s0
	s_nop 0

; __device__ __forceinline__ unsigned xb_ld(unsigned* p)              { return __hip_atomic_load(p, __ATOMIC_RELAXED, __HIP_MEMORY_SCOPE_AGENT); }
; __device__ __forceinline__ unsigned xb_add(unsigned* p, unsigned v) { return __hip_atomic_fetch_add(p, v, __ATOMIC_RELAXED, __HIP_MEMORY_SCOPE_AGENT); }
; #define XB_SPIN(cond, bar) do { unsigned _sp = 0; while (cond) { __builtin_amdgcn_s_sleep(1); \
;     if ((++_sp & 255u) == 0u) { if (xb_ld(&(bar)[XB_TMO])) break; if (_sp > XB_SPIN_CAP) { atomicAdd(&(bar)[XB_TMO], 1u); break; } } } } while (0)
; __device__ __forceinline__ void xcd_barrier(const XcdBarrier& b) {
;     ...
;         const unsigned old = xb_add(&bar[XB_XSUB(b.x)], 1u);
;         const unsigned gen = old / nloc;
;         if (old + 1u == (gen + 1u) * nloc) {
;             __builtin_amdgcn_fence(__ATOMIC_RELEASE, "agent");
;             asm volatile("s_waitcnt vmcnt(0)" ::: "memory");
;             const unsigned og = xb_add(&bar[XB_TOP], 1u);
;             const unsigned tg = og / nx;
;             if (og + 1u == (tg + 1u) * nx) xb_add(&bar[XB_TOPGEN], 1u);
;             else XB_SPIN(xb_ld(&bar[XB_TOPGEN]) == tg, bar);
;             __builtin_amdgcn_fence(__ATOMIC_ACQUIRE, "agent");
;             xb_add(&bar[XB_XGEN(b.x)], 1u);
;             asm volatile("s_waitcnt vmcnt(0)" ::: "memory");
;         } else {
;             XB_SPIN(xb_ld(&bar[XB_XGEN(b.x)]) == gen, bar);
.LBB0_1158:
	s_or_b64 exec, exec, s[12:13]
	buffer_inv sc1
	v_cvt_f32_u32_e32 v4, v2
	s_waitcnt vmcnt(0)
	v_readfirstlane_b32 s0, v3
	v_sub_u32_e32 v3, 0, v2
	v_rcp_iflag_f32_e32 v4, v4
	v_add_u32_e32 v5, s0, v1
	v_mul_f32_e32 v4, 0x4f7ffffe, v4
	v_cvt_u32_f32_e32 v4, v4
	v_mul_lo_u32 v1, v3, v4
	v_mul_hi_u32 v1, v4, v1
	v_add_u32_e32 v1, v4, v1
	v_mul_hi_u32 v1, v5, v1
	v_mul_lo_u32 v3, v1, v2
	v_sub_u32_e32 v3, v5, v3
	v_add_u32_e32 v4, 1, v1
	v_cmp_ge_u32_e32 vcc, v3, v2
	s_nop 1
	v_cndmask_b32_e32 v1, v1, v4, vcc
	v_sub_u32_e32 v4, v3, v2
	v_cndmask_b32_e32 v3, v3, v4, vcc
	v_add_u32_e32 v4, 1, v1
	v_cmp_ge_u32_e32 vcc, v3, v2
	v_add_u32_e32 v3, 1, v5
	s_nop 0
	v_cndmask_b32_e32 v1, v1, v4, vcc
	v_mul_lo_u32 v4, v2, v1
	v_add_u32_e32 v2, v4, v2
	v_cmp_ne_u32_e32 vcc, v3, v2
	s_and_saveexec_b64 s[0:1], vcc
	s_xor_b64 s[0:1], exec, s[0:1]
	s_cbranch_execz .LBB0_1172
	s_waitcnt lgkmcnt(0)
	v_mov_b32_e32 v0, 0x2000
	global_load_dword v0, v0, s[10:11] offset:1024 sc1
	s_add_u32 s18, s10, 0x2400
	s_addc_u32 s19, s11, 0
	s_waitcnt vmcnt(0)
	v_cmp_eq_u32_e32 vcc, v0, v1
	s_and_saveexec_b64 s[12:13], vcc
	s_cbranch_execz .LBB0_1171
	s_add_u32 s14, s84, 0xc10200
	s_addc_u32 s15, s85, 0
	s_mov_b32 s4, 1
	s_mov_b64 s[36:37], 0
	v_mov_b32_e32 v0, 0
	s_branch .LBB0_1162

; __device__ __forceinline__ unsigned xb_ld(unsigned* p)              { return __hip_atomic_load(p, __ATOMIC_RELAXED, __HIP_MEMORY_SCOPE_AGENT); }
; __device__ __forceinline__ unsigned xb_add(unsigned* p, unsigned v) { return __hip_atomic_fetch_add(p, v, __ATOMIC_RELAXED, __HIP_MEMORY_SCOPE_AGENT); }
; #define XB_SPIN(cond, bar) do { unsigned _sp = 0; while (cond) { __builtin_amdgcn_s_sleep(1); \
;     if ((++_sp & 255u) == 0u) { if (xb_ld(&(bar)[XB_TMO])) break; if (_sp > XB_SPIN_CAP) { atomicAdd(&(bar)[XB_TMO], 1u); break; } } } } while (0)
; __device__ __forceinline__ void xcd_barrier(const XcdBarrier& b) {
;     ...
;         const unsigned old = xb_add(&bar[XB_XSUB(b.x)], 1u);
;         const unsigned gen = old / nloc;
;         if (old + 1u == (gen + 1u) * nloc) {
;             __builtin_amdgcn_fence(__ATOMIC_RELEASE, "agent");
;             asm volatile("s_waitcnt vmcnt(0)" ::: "memory");
;             const unsigned og = xb_add(&bar[XB_TOP], 1u);
;             const unsigned tg = og / nx;
;             if (og + 1u == (tg + 1u) * nx) xb_add(&bar[XB_TOPGEN], 1u);
;             else XB_SPIN(xb_ld(&bar[XB_TOPGEN]) == tg, bar);
;             __builtin_amdgcn_fence(__ATOMIC_ACQUIRE, "agent");
;             xb_add(&bar[XB_XGEN(b.x)], 1u);
;             asm volatile("s_waitcnt vmcnt(0)" ::: "memory");
;         } else {
;             XB_SPIN(xb_ld(&bar[XB_XGEN(b.x)]) == gen, bar);
.LBB0_1255:
	s_or_b64 exec, exec, s[10:11]
	buffer_inv sc1
	v_cvt_f32_u32_e32 v4, v2
	s_waitcnt vmcnt(0)
	v_readfirstlane_b32 s0, v3
	v_sub_u32_e32 v3, 0, v2
	v_rcp_iflag_f32_e32 v4, v4
	v_add_u32_e32 v5, s0, v1
	v_mul_f32_e32 v4, 0x4f7ffffe, v4
	v_cvt_u32_f32_e32 v4, v4
	v_mul_lo_u32 v1, v3, v4
	v_mul_hi_u32 v1, v4, v1
	v_add_u32_e32 v1, v4, v1
	v_mul_hi_u32 v1, v5, v1
	v_mul_lo_u32 v3, v1, v2
	v_sub_u32_e32 v3, v5, v3
	v_add_u32_e32 v4, 1, v1
	v_cmp_ge_u32_e32 vcc, v3, v2
	s_nop 1
	v_cndmask_b32_e32 v1, v1, v4, vcc
	v_sub_u32_e32 v4, v3, v2
	v_cndmask_b32_e32 v3, v3, v4, vcc
	v_add_u32_e32 v4, 1, v1
	v_cmp_ge_u32_e32 vcc, v3, v2
	v_add_u32_e32 v3, 1, v5
	s_nop 0
	v_cndmask_b32_e32 v1, v1, v4, vcc
	v_mul_lo_u32 v4, v2, v1
	v_add_u32_e32 v2, v4, v2
	v_cmp_ne_u32_e32 vcc, v3, v2
	s_and_saveexec_b64 s[0:1], vcc
	s_xor_b64 s[0:1], exec, s[0:1]
	s_cbranch_execz .LBB0_1269
	s_waitcnt lgkmcnt(0)
	v_mov_b32_e32 v0, 0x2000
	global_load_dword v0, v0, s[8:9] offset:1024 sc1
	s_add_u32 s14, s8, 0x2400
	s_addc_u32 s15, s9, 0
	s_waitcnt vmcnt(0)
	v_cmp_eq_u32_e32 vcc, v0, v1
	s_and_saveexec_b64 s[10:11], vcc
	s_cbranch_execz .LBB0_1268
	s_add_u32 s12, s84, 0xc10200
	s_addc_u32 s13, s85, 0
	s_mov_b32 s4, 1
	s_mov_b64 s[22:23], 0
	v_mov_b32_e32 v0, 0
	s_branch .LBB0_1259

; __device__ __forceinline__ unsigned xb_ld(unsigned* p)              { return __hip_atomic_load(p, __ATOMIC_RELAXED, __HIP_MEMORY_SCOPE_AGENT); }
; __device__ __forceinline__ unsigned xb_add(unsigned* p, unsigned v) { return __hip_atomic_fetch_add(p, v, __ATOMIC_RELAXED, __HIP_MEMORY_SCOPE_AGENT); }
; #define XB_SPIN(cond, bar) do { unsigned _sp = 0; while (cond) { __builtin_amdgcn_s_sleep(1); \
;     if ((++_sp & 255u) == 0u) { if (xb_ld(&(bar)[XB_TMO])) break; if (_sp > XB_SPIN_CAP) { atomicAdd(&(bar)[XB_TMO], 1u); break; } } } } while (0)
; __device__ __forceinline__ void xcd_barrier(const XcdBarrier& b) {
;     ...
;         const unsigned old = xb_add(&bar[XB_XSUB(b.x)], 1u);
;         const unsigned gen = old / nloc;
;         if (old + 1u == (gen + 1u) * nloc) {
;             __builtin_amdgcn_fence(__ATOMIC_RELEASE, "agent");
;             asm volatile("s_waitcnt vmcnt(0)" ::: "memory");
;             const unsigned og = xb_add(&bar[XB_TOP], 1u);
;             const unsigned tg = og / nx;
;             if (og + 1u == (tg + 1u) * nx) xb_add(&bar[XB_TOPGEN], 1u);
;             else XB_SPIN(xb_ld(&bar[XB_TOPGEN]) == tg, bar);
;             __builtin_amdgcn_fence(__ATOMIC_ACQUIRE, "agent");
;             xb_add(&bar[XB_XGEN(b.x)], 1u);
;             asm volatile("s_waitcnt vmcnt(0)" ::: "memory");
;         } else {
;             XB_SPIN(xb_ld(&bar[XB_XGEN(b.x)]) == gen, bar);
.LBB0_1336:
	s_or_b64 exec, exec, s[10:11]
	buffer_inv sc1
	v_cvt_f32_u32_e32 v4, v2
	s_waitcnt vmcnt(0)
	v_readfirstlane_b32 s0, v3
	v_sub_u32_e32 v3, 0, v2
	v_rcp_iflag_f32_e32 v4, v4
	v_add_u32_e32 v5, s0, v1
	v_mul_f32_e32 v4, 0x4f7ffffe, v4
	v_cvt_u32_f32_e32 v4, v4
	v_mul_lo_u32 v1, v3, v4
	v_mul_hi_u32 v1, v4, v1
	v_add_u32_e32 v1, v4, v1
	v_mul_hi_u32 v1, v5, v1
	v_mul_lo_u32 v3, v1, v2
	v_sub_u32_e32 v3, v5, v3
	v_add_u32_e32 v4, 1, v1
	v_cmp_ge_u32_e32 vcc, v3, v2
	s_nop 1
	v_cndmask_b32_e32 v1, v1, v4, vcc
	v_sub_u32_e32 v4, v3, v2
	v_cndmask_b32_e32 v3, v3, v4, vcc
	v_add_u32_e32 v4, 1, v1
	v_cmp_ge_u32_e32 vcc, v3, v2
	v_add_u32_e32 v3, 1, v5
	s_nop 0
	v_cndmask_b32_e32 v1, v1, v4, vcc
	v_mul_lo_u32 v4, v2, v1
	v_add_u32_e32 v2, v4, v2
	v_cmp_ne_u32_e32 vcc, v3, v2
	s_and_saveexec_b64 s[0:1], vcc
	s_xor_b64 s[0:1], exec, s[0:1]
	s_cbranch_execz .LBB0_1350
	s_waitcnt lgkmcnt(0)
	v_mov_b32_e32 v0, 0x2000
	global_load_dword v0, v0, s[8:9] offset:1024 sc1
	s_add_u32 s14, s8, 0x2400
	s_addc_u32 s15, s9, 0
	s_waitcnt vmcnt(0)
	v_cmp_eq_u32_e32 vcc, v0, v1
	s_and_saveexec_b64 s[10:11], vcc
	s_cbranch_execz .LBB0_1349
	s_add_u32 s12, s84, 0xc10200
	s_addc_u32 s13, s85, 0
	s_mov_b32 s3, 1
	s_mov_b64 s[18:19], 0
	v_mov_b32_e32 v0, 0
	s_branch .LBB0_1340

; __device__ __forceinline__ unsigned xb_ld(unsigned* p)              { return __hip_atomic_load(p, __ATOMIC_RELAXED, __HIP_MEMORY_SCOPE_AGENT); }
; __device__ __forceinline__ unsigned xb_add(unsigned* p, unsigned v) { return __hip_atomic_fetch_add(p, v, __ATOMIC_RELAXED, __HIP_MEMORY_SCOPE_AGENT); }
; #define XB_SPIN(cond, bar) do { unsigned _sp = 0; while (cond) { __builtin_amdgcn_s_sleep(1); \
;     if ((++_sp & 255u) == 0u) { if (xb_ld(&(bar)[XB_TMO])) break; if (_sp > XB_SPIN_CAP) { atomicAdd(&(bar)[XB_TMO], 1u); break; } } } } while (0)
; __device__ __forceinline__ void xcd_barrier(const XcdBarrier& b) {
;     ...
;         const unsigned old = xb_add(&bar[XB_XSUB(b.x)], 1u);
;         const unsigned gen = old / nloc;
;         if (old + 1u == (gen + 1u) * nloc) {
;             __builtin_amdgcn_fence(__ATOMIC_RELEASE, "agent");
;             asm volatile("s_waitcnt vmcnt(0)" ::: "memory");
;             const unsigned og = xb_add(&bar[XB_TOP], 1u);
;             const unsigned tg = og / nx;
;             if (og + 1u == (tg + 1u) * nx) xb_add(&bar[XB_TOPGEN], 1u);
;             else XB_SPIN(xb_ld(&bar[XB_TOPGEN]) == tg, bar);
;             __builtin_amdgcn_fence(__ATOMIC_ACQUIRE, "agent");
;             xb_add(&bar[XB_XGEN(b.x)], 1u);
;             asm volatile("s_waitcnt vmcnt(0)" ::: "memory");
;         } else {
;             XB_SPIN(xb_ld(&bar[XB_XGEN(b.x)]) == gen, bar);
.LBB0_1408:
	s_or_b64 exec, exec, s[8:9]
	buffer_inv sc1
	v_cvt_f32_u32_e32 v4, v2
	s_waitcnt vmcnt(0)
	v_readfirstlane_b32 s4, v3
	v_sub_u32_e32 v3, 0, v2
	v_rcp_iflag_f32_e32 v4, v4
	v_add_u32_e32 v5, s4, v1
	v_mul_f32_e32 v4, 0x4f7ffffe, v4
	v_cvt_u32_f32_e32 v4, v4
	v_mul_lo_u32 v1, v3, v4
	v_mul_hi_u32 v1, v4, v1
	v_add_u32_e32 v1, v4, v1
	v_mul_hi_u32 v1, v5, v1
	v_mul_lo_u32 v3, v1, v2
	v_sub_u32_e32 v3, v5, v3
	v_add_u32_e32 v4, 1, v1
	v_cmp_ge_u32_e32 vcc, v3, v2
	s_nop 1
	v_cndmask_b32_e32 v1, v1, v4, vcc
	v_sub_u32_e32 v4, v3, v2
	v_cndmask_b32_e32 v3, v3, v4, vcc
	v_add_u32_e32 v4, 1, v1
	v_cmp_ge_u32_e32 vcc, v3, v2
	v_add_u32_e32 v3, 1, v5
	s_nop 0
	v_cndmask_b32_e32 v1, v1, v4, vcc
	v_mul_lo_u32 v4, v2, v1
	v_add_u32_e32 v2, v4, v2
	v_cmp_ne_u32_e32 vcc, v3, v2
	s_and_saveexec_b64 s[4:5], vcc
	s_xor_b64 s[4:5], exec, s[4:5]
	s_cbranch_execz .LBB0_1422
	s_waitcnt lgkmcnt(0)
	v_mov_b32_e32 v0, 0x2000
	global_load_dword v0, v0, s[0:1] offset:1024 sc1
	s_add_u32 s12, s0, 0x2400
	s_addc_u32 s13, s1, 0
	s_waitcnt vmcnt(0)
	v_cmp_eq_u32_e32 vcc, v0, v1
	s_and_saveexec_b64 s[8:9], vcc
	s_cbranch_execz .LBB0_1421
	s_add_u32 s10, s84, 0xc10200
	s_addc_u32 s11, s85, 0
	s_mov_b32 s16, 1
	s_mov_b64 s[14:15], 0
	v_mov_b32_e32 v0, 0
	s_branch .LBB0_1412

; __device__ __forceinline__ unsigned xb_ld(unsigned* p)              { return __hip_atomic_load(p, __ATOMIC_RELAXED, __HIP_MEMORY_SCOPE_AGENT); }
; __device__ __forceinline__ unsigned xb_add(unsigned* p, unsigned v) { return __hip_atomic_fetch_add(p, v, __ATOMIC_RELAXED, __HIP_MEMORY_SCOPE_AGENT); }
; #define XB_SPIN(cond, bar) do { unsigned _sp = 0; while (cond) { __builtin_amdgcn_s_sleep(1); \
;     if ((++_sp & 255u) == 0u) { if (xb_ld(&(bar)[XB_TMO])) break; if (_sp > XB_SPIN_CAP) { atomicAdd(&(bar)[XB_TMO], 1u); break; } } } } while (0)
; __device__ __forceinline__ void xcd_barrier(const XcdBarrier& b) {
;     ...
;             if (og + 1u == (tg + 1u) * nx) xb_add(&bar[XB_TOPGEN], 1u);
;             else XB_SPIN(xb_ld(&bar[XB_TOPGEN]) == tg, bar);
;             __builtin_amdgcn_fence(__ATOMIC_ACQUIRE, "agent");
;             xb_add(&bar[XB_XGEN(b.x)], 1u);
;             asm volatile("s_waitcnt vmcnt(0)" ::: "memory");
.LBB0_1439:
	s_or_b64 exec, exec, s[4:5]
	s_mov_b64 s[4:5], exec
	v_mbcnt_lo_u32_b32 v0, s4, 0
	v_mbcnt_hi_u32_b32 v0, s5, v0
	v_cmp_eq_u32_e32 vcc, 0, v0
	s_waitcnt vmcnt(0)
	s_nop 0
	s_and_saveexec_b64 s[8:9], vcc
	s_cbranch_execz .LBB0_1441
	s_bcnt1_i32_b64 s4, s[4:5]
	v_mov_b32_e32 v0, 0x2000
	v_mov_b32_e32 v1, s4
	s_nop 0
